# norm-phase transpose item edge paths: non-temporal hint on their streamed f32 loads
# baseline (speedup 1.0000x reference)
.LBB0_105:
	s_andn2_b64 vcc, exec, s[0:1]
	s_cbranch_vccnz .LBB0_139
	s_waitcnt lgkmcnt(0)
	v_mov_b32_e32 v8, v193
	s_and_b32 s21, s18, 0x3c0
	s_and_b32 s20, s17, 0x3c0
	v_ashrrev_i32_e32 v9, 6, v8
	s_lshl_b32 s0, s21, 2
	s_waitcnt lgkmcnt(3)
	v_and_b32_e32 v10, 63, v8
	s_add_u32 s0, s10, s0
	v_add_u32_e32 v4, s20, v9
	s_addc_u32 s1, s11, 0
	v_lshlrev_b32_e32 v0, 2, v10
	v_ashrrev_i32_e32 v5, 31, v4
	v_lshl_add_u64 v[2:3], s[0:1], 0, v[0:1]
	v_lshlrev_b64 v[6:7], 12, v[4:5]
	v_lshl_add_u64 v[6:7], v[2:3], 0, v[6:7]
	s_waitcnt lgkmcnt(0)
	s_barrier
	global_load_dword v11, v[6:7], off nt
	v_readlane_b32 s22, v252, 41
	v_readlane_b32 s23, v252, 42
	s_andn2_b64 vcc, exec, s[22:23]
	v_lshl_add_u64 v[6:7], v[4:5], 2, s[4:5]
	v_cndmask_b32_e64 v0, 0, 1, s[22:23]
	v_cmp_ne_u32_e64 s[0:1], 1, v0
	s_cbranch_vccnz .LBB0_108
	global_load_dword v0, v[6:7], off nt
	s_waitcnt vmcnt(0)
	v_mul_f32_e32 v11, v11, v0
.LBB0_108:
	v_add_u32_e32 v12, 4, v4
	v_ashrrev_i32_e32 v13, 31, v12
	v_lshlrev_b64 v[12:13], 12, v[12:13]
	v_lshl_add_u64 v[12:13], v[2:3], 0, v[12:13]
	global_load_dword v5, v[12:13], off nt
	s_movk_i32 s22, 0x104
	v_lshl_add_u32 v0, v10, 2, 0
	v_mul_lo_u32 v9, v9, s22
	v_add_u32_e32 v0, v0, v9
	s_and_b64 vcc, exec, s[0:1]
	s_waitcnt vmcnt(1)
	ds_write_b32 v0, v11
	s_cbranch_vccnz .LBB0_110
	global_load_dword v9, v[6:7], off offset:16 nt
	s_waitcnt vmcnt(0)
	v_mul_f32_e32 v5, v5, v9
.LBB0_110:
	v_add_u32_e32 v10, 8, v4
	v_ashrrev_i32_e32 v11, 31, v10
	v_lshlrev_b64 v[10:11], 12, v[10:11]
	v_lshl_add_u64 v[10:11], v[2:3], 0, v[10:11]
	global_load_dword v9, v[10:11], off nt
	s_and_b64 vcc, exec, s[0:1]
	s_waitcnt vmcnt(1)
	ds_write_b32 v0, v5 offset:1040
	s_cbranch_vccnz .LBB0_112
	global_load_dword v5, v[6:7], off offset:32 nt
	s_waitcnt vmcnt(0)
	v_mul_f32_e32 v9, v9, v5
.LBB0_112:
	v_add_u32_e32 v10, 12, v4
	v_ashrrev_i32_e32 v11, 31, v10
	v_lshlrev_b64 v[10:11], 12, v[10:11]
	v_lshl_add_u64 v[10:11], v[2:3], 0, v[10:11]
	global_load_dword v5, v[10:11], off nt
	s_and_b64 vcc, exec, s[0:1]
	s_waitcnt vmcnt(1)
	ds_write_b32 v0, v9 offset:2080
	s_cbranch_vccnz .LBB0_114
	global_load_dword v9, v[6:7], off offset:48 nt
	s_waitcnt vmcnt(0)
	v_mul_f32_e32 v5, v5, v9
.LBB0_114:
	v_add_u32_e32 v10, 16, v4
	v_ashrrev_i32_e32 v11, 31, v10
	v_lshlrev_b64 v[10:11], 12, v[10:11]
	v_lshl_add_u64 v[10:11], v[2:3], 0, v[10:11]
	global_load_dword v9, v[10:11], off nt
	s_and_b64 vcc, exec, s[0:1]
	s_waitcnt vmcnt(1)
	ds_write_b32 v0, v5 offset:3120
	s_cbranch_vccnz .LBB0_116
	global_load_dword v5, v[6:7], off offset:64 nt
	s_waitcnt vmcnt(0)
	v_mul_f32_e32 v9, v9, v5
.LBB0_116:
	v_add_u32_e32 v10, 20, v4
	v_ashrrev_i32_e32 v11, 31, v10
	v_lshlrev_b64 v[10:11], 12, v[10:11]
	v_lshl_add_u64 v[10:11], v[2:3], 0, v[10:11]
	global_load_dword v5, v[10:11], off nt
	s_and_b64 vcc, exec, s[0:1]
	s_waitcnt vmcnt(1)
	ds_write_b32 v0, v9 offset:4160
	s_cbranch_vccnz .LBB0_118
	global_load_dword v9, v[6:7], off offset:80 nt
	s_waitcnt vmcnt(0)
	v_mul_f32_e32 v5, v5, v9
.LBB0_118:
	v_add_u32_e32 v10, 24, v4
	v_ashrrev_i32_e32 v11, 31, v10
	v_lshlrev_b64 v[10:11], 12, v[10:11]
	v_lshl_add_u64 v[10:11], v[2:3], 0, v[10:11]
	global_load_dword v9, v[10:11], off nt
	s_and_b64 vcc, exec, s[0:1]
	s_waitcnt vmcnt(1)
	ds_write_b32 v0, v5 offset:5200
	s_cbranch_vccnz .LBB0_120
	global_load_dword v5, v[6:7], off offset:96 nt
	s_waitcnt vmcnt(0)
	v_mul_f32_e32 v9, v9, v5
.LBB0_120:
	v_add_u32_e32 v10, 28, v4
	v_ashrrev_i32_e32 v11, 31, v10
	v_lshlrev_b64 v[10:11], 12, v[10:11]
	v_lshl_add_u64 v[10:11], v[2:3], 0, v[10:11]
	global_load_dword v5, v[10:11], off nt
	s_and_b64 vcc, exec, s[0:1]
	s_waitcnt vmcnt(1)
	ds_write_b32 v0, v9 offset:6240
	s_cbranch_vccnz .LBB0_122
	global_load_dword v9, v[6:7], off offset:112 nt
	s_waitcnt vmcnt(0)
	v_mul_f32_e32 v5, v5, v9
.LBB0_122:
	v_add_u32_e32 v10, 32, v4
	v_ashrrev_i32_e32 v11, 31, v10
	v_lshlrev_b64 v[10:11], 12, v[10:11]
	v_lshl_add_u64 v[10:11], v[2:3], 0, v[10:11]
	global_load_dword v9, v[10:11], off nt
	s_and_b64 vcc, exec, s[0:1]
	s_waitcnt vmcnt(1)
	ds_write_b32 v0, v5 offset:7280
	s_cbranch_vccnz .LBB0_124
	global_load_dword v5, v[6:7], off offset:128 nt
	s_waitcnt vmcnt(0)
	v_mul_f32_e32 v9, v9, v5
.LBB0_124:
	v_add_u32_e32 v10, 36, v4
	v_ashrrev_i32_e32 v11, 31, v10
	v_lshlrev_b64 v[10:11], 12, v[10:11]
	v_lshl_add_u64 v[10:11], v[2:3], 0, v[10:11]
	global_load_dword v5, v[10:11], off nt
	s_and_b64 vcc, exec, s[0:1]
	s_waitcnt vmcnt(1)
	ds_write_b32 v0, v9 offset:8320
	s_cbranch_vccnz .LBB0_126
	global_load_dword v9, v[6:7], off offset:144 nt
	s_waitcnt vmcnt(0)
	v_mul_f32_e32 v5, v5, v9
.LBB0_126:
	v_add_u32_e32 v10, 40, v4
	v_ashrrev_i32_e32 v11, 31, v10
	v_lshlrev_b64 v[10:11], 12, v[10:11]
	v_lshl_add_u64 v[10:11], v[2:3], 0, v[10:11]
	global_load_dword v9, v[10:11], off nt
	s_and_b64 vcc, exec, s[0:1]
	s_waitcnt vmcnt(1)
	ds_write_b32 v0, v5 offset:9360
	s_cbranch_vccnz .LBB0_128
	global_load_dword v5, v[6:7], off offset:160 nt
	s_waitcnt vmcnt(0)
	v_mul_f32_e32 v9, v9, v5
.LBB0_128:
	v_add_u32_e32 v10, 44, v4
	v_ashrrev_i32_e32 v11, 31, v10
	v_lshlrev_b64 v[10:11], 12, v[10:11]
	v_lshl_add_u64 v[10:11], v[2:3], 0, v[10:11]
	global_load_dword v5, v[10:11], off nt
	s_and_b64 vcc, exec, s[0:1]
	s_waitcnt vmcnt(1)
	ds_write_b32 v0, v9 offset:10400
	s_cbranch_vccnz .LBB0_130
	global_load_dword v9, v[6:7], off offset:176 nt
	s_waitcnt vmcnt(0)
	v_mul_f32_e32 v5, v5, v9
.LBB0_130:
	v_add_u32_e32 v10, 48, v4
	v_ashrrev_i32_e32 v11, 31, v10
	v_lshlrev_b64 v[10:11], 12, v[10:11]
	v_lshl_add_u64 v[10:11], v[2:3], 0, v[10:11]
	global_load_dword v9, v[10:11], off nt
	s_and_b64 vcc, exec, s[0:1]
	s_waitcnt vmcnt(1)
	ds_write_b32 v0, v5 offset:11440
	s_cbranch_vccnz .LBB0_132
	global_load_dword v5, v[6:7], off offset:192 nt
	s_waitcnt vmcnt(0)
	v_mul_f32_e32 v9, v9, v5
.LBB0_132:
	v_add_u32_e32 v10, 52, v4
	v_ashrrev_i32_e32 v11, 31, v10
	v_lshlrev_b64 v[10:11], 12, v[10:11]
	v_lshl_add_u64 v[10:11], v[2:3], 0, v[10:11]
	global_load_dword v5, v[10:11], off nt
	s_and_b64 vcc, exec, s[0:1]
	s_waitcnt vmcnt(1)
	ds_write_b32 v0, v9 offset:12480
	s_cbranch_vccnz .LBB0_134
	global_load_dword v9, v[6:7], off offset:208 nt
	s_waitcnt vmcnt(0)
	v_mul_f32_e32 v5, v5, v9
.LBB0_134:
	v_add_u32_e32 v10, 56, v4
	v_ashrrev_i32_e32 v11, 31, v10
	v_lshlrev_b64 v[10:11], 12, v[10:11]
	v_lshl_add_u64 v[10:11], v[2:3], 0, v[10:11]
	global_load_dword v9, v[10:11], off nt
	s_and_b64 vcc, exec, s[0:1]
	s_waitcnt vmcnt(1)
	ds_write_b32 v0, v5 offset:13520
	s_cbranch_vccnz .LBB0_136
	global_load_dword v5, v[6:7], off offset:224 nt
	s_waitcnt vmcnt(0)
	v_mul_f32_e32 v9, v9, v5
.LBB0_136:
	v_add_u32_e32 v4, 60, v4
	v_ashrrev_i32_e32 v5, 31, v4
	v_lshlrev_b64 v[4:5], 12, v[4:5]
	v_lshl_add_u64 v[2:3], v[2:3], 0, v[4:5]
	global_load_dword v2, v[2:3], off nt
	s_and_b64 vcc, exec, s[0:1]
	s_waitcnt vmcnt(1)
	ds_write_b32 v0, v9 offset:14560
	s_cbranch_vccnz .LBB0_138
	global_load_dword v3, v[6:7], off offset:240 nt
	s_waitcnt vmcnt(0)
	v_mul_f32_e32 v2, v2, v3

.LBB0_140:
	s_andn2_b64 vcc, exec, s[0:1]
	s_cbranch_vccnz .LBB0_174
	s_add_i32 s0, s19, 0xfff0
	s_and_b32 s1, s0, 0xff
	s_mulk_i32 s1, 0xab
	s_bfe_u32 s1, s1, 0x5000b
	s_mul_i32 s20, s1, 12
	s_sub_i32 s0, s0, s20
	s_and_b32 s21, s0, 0xff
	s_waitcnt lgkmcnt(0)
	v_mov_b32_e32 v8, v193
	s_lshl_b32 s20, s1, 6
	s_lshl_b32 s0, s21, 8
	s_add_u32 s0, s12, s0
	s_waitcnt lgkmcnt(3)
	v_and_b32_e32 v10, 63, v8
	v_ashrrev_i32_e32 v9, 6, v8
	s_addc_u32 s1, s13, 0
	v_lshlrev_b32_e32 v0, 2, v10
	v_lshl_add_u64 v[2:3], s[0:1], 0, v[0:1]
	v_add_u32_e32 v4, s20, v9
	s_movk_i32 s0, 0xc00
	v_mad_i64_i32 v[6:7], s[0:1], v4, s0, v[2:3]
	s_waitcnt lgkmcnt(0)
	s_barrier
	global_load_dword v11, v[6:7], off nt
	v_readlane_b32 s22, v252, 43
	v_readlane_b32 s23, v252, 44
	v_ashrrev_i32_e32 v5, 31, v4
	s_andn2_b64 vcc, exec, s[22:23]
	v_cndmask_b32_e64 v0, 0, 1, s[22:23]
	v_cmp_ne_u32_e64 s[0:1], 1, v0
	v_lshl_add_u64 v[6:7], v[4:5], 2, s[8:9]
	s_cbranch_vccnz .LBB0_143
	global_load_dword v0, v[6:7], off nt
	s_waitcnt vmcnt(0)
	v_mul_f32_e32 v11, v11, v0
.LBB0_143:
	v_add_u32_e32 v0, 4, v4
	s_movk_i32 s22, 0xc00
	v_mad_i64_i32 v[12:13], s[22:23], v0, s22, v[2:3]
	global_load_dword v5, v[12:13], off nt
	s_movk_i32 s22, 0x104
	v_lshl_add_u32 v0, v10, 2, 0
	v_mul_lo_u32 v9, v9, s22
	v_add_u32_e32 v0, v0, v9
	s_and_b64 vcc, exec, s[0:1]
	s_waitcnt vmcnt(1)
	ds_write_b32 v0, v11
	s_cbranch_vccnz .LBB0_145
	global_load_dword v9, v[6:7], off offset:16 nt
	s_waitcnt vmcnt(0)
	v_mul_f32_e32 v5, v5, v9
.LBB0_145:
	v_add_u32_e32 v9, 8, v4
	s_movk_i32 s22, 0xc00
	v_mad_i64_i32 v[10:11], s[22:23], v9, s22, v[2:3]
	global_load_dword v9, v[10:11], off nt
	s_and_b64 vcc, exec, s[0:1]
	s_waitcnt vmcnt(1)
	ds_write_b32 v0, v5 offset:1040
	s_cbranch_vccnz .LBB0_147
	global_load_dword v5, v[6:7], off offset:32 nt
	s_waitcnt vmcnt(0)
	v_mul_f32_e32 v9, v9, v5
.LBB0_147:
	v_add_u32_e32 v5, 12, v4
	s_movk_i32 s22, 0xc00
	v_mad_i64_i32 v[10:11], s[22:23], v5, s22, v[2:3]
	global_load_dword v5, v[10:11], off nt
	s_and_b64 vcc, exec, s[0:1]
	s_waitcnt vmcnt(1)
	ds_write_b32 v0, v9 offset:2080
	s_cbranch_vccnz .LBB0_149
	global_load_dword v9, v[6:7], off offset:48 nt
	s_waitcnt vmcnt(0)
	v_mul_f32_e32 v5, v5, v9
.LBB0_149:
	v_add_u32_e32 v9, 16, v4
	s_movk_i32 s22, 0xc00
	v_mad_i64_i32 v[10:11], s[22:23], v9, s22, v[2:3]
	global_load_dword v9, v[10:11], off nt
	s_and_b64 vcc, exec, s[0:1]
	s_waitcnt vmcnt(1)
	ds_write_b32 v0, v5 offset:3120
	s_cbranch_vccnz .LBB0_151
	global_load_dword v5, v[6:7], off offset:64 nt
	s_waitcnt vmcnt(0)
	v_mul_f32_e32 v9, v9, v5
.LBB0_151:
	v_add_u32_e32 v5, 20, v4
	s_movk_i32 s22, 0xc00
	v_mad_i64_i32 v[10:11], s[22:23], v5, s22, v[2:3]
	global_load_dword v5, v[10:11], off nt
	s_and_b64 vcc, exec, s[0:1]
	s_waitcnt vmcnt(1)
	ds_write_b32 v0, v9 offset:4160
	s_cbranch_vccnz .LBB0_153
	global_load_dword v9, v[6:7], off offset:80 nt
	s_waitcnt vmcnt(0)
	v_mul_f32_e32 v5, v5, v9
.LBB0_153:
	v_add_u32_e32 v9, 24, v4
	s_movk_i32 s22, 0xc00
	v_mad_i64_i32 v[10:11], s[22:23], v9, s22, v[2:3]
	global_load_dword v9, v[10:11], off nt
	s_and_b64 vcc, exec, s[0:1]
	s_waitcnt vmcnt(1)
	ds_write_b32 v0, v5 offset:5200
	s_cbranch_vccnz .LBB0_155
	global_load_dword v5, v[6:7], off offset:96 nt
	s_waitcnt vmcnt(0)
	v_mul_f32_e32 v9, v9, v5
.LBB0_155:
	v_add_u32_e32 v5, 28, v4
	s_movk_i32 s22, 0xc00
	v_mad_i64_i32 v[10:11], s[22:23], v5, s22, v[2:3]
	global_load_dword v5, v[10:11], off nt
	s_and_b64 vcc, exec, s[0:1]
	s_waitcnt vmcnt(1)
	ds_write_b32 v0, v9 offset:6240
	s_cbranch_vccnz .LBB0_157
	global_load_dword v9, v[6:7], off offset:112 nt
	s_waitcnt vmcnt(0)
	v_mul_f32_e32 v5, v5, v9
.LBB0_157:
	v_add_u32_e32 v9, 32, v4
	s_movk_i32 s22, 0xc00
	v_mad_i64_i32 v[10:11], s[22:23], v9, s22, v[2:3]
	global_load_dword v9, v[10:11], off nt
	s_and_b64 vcc, exec, s[0:1]
	s_waitcnt vmcnt(1)
	ds_write_b32 v0, v5 offset:7280
	s_cbranch_vccnz .LBB0_159
	global_load_dword v5, v[6:7], off offset:128 nt
	s_waitcnt vmcnt(0)
	v_mul_f32_e32 v9, v9, v5
.LBB0_159:
	v_add_u32_e32 v5, 36, v4
	s_movk_i32 s22, 0xc00
	v_mad_i64_i32 v[10:11], s[22:23], v5, s22, v[2:3]
	global_load_dword v5, v[10:11], off nt
	s_and_b64 vcc, exec, s[0:1]
	s_waitcnt vmcnt(1)
	ds_write_b32 v0, v9 offset:8320
	s_cbranch_vccnz .LBB0_161
	global_load_dword v9, v[6:7], off offset:144 nt
	s_waitcnt vmcnt(0)
	v_mul_f32_e32 v5, v5, v9
.LBB0_161:
	v_add_u32_e32 v9, 40, v4
	s_movk_i32 s22, 0xc00
	v_mad_i64_i32 v[10:11], s[22:23], v9, s22, v[2:3]
	global_load_dword v9, v[10:11], off nt
	s_and_b64 vcc, exec, s[0:1]
	s_waitcnt vmcnt(1)
	ds_write_b32 v0, v5 offset:9360
	s_cbranch_vccnz .LBB0_163
	global_load_dword v5, v[6:7], off offset:160 nt
	s_waitcnt vmcnt(0)
	v_mul_f32_e32 v9, v9, v5
.LBB0_163:
	v_add_u32_e32 v5, 44, v4
	s_movk_i32 s22, 0xc00
	v_mad_i64_i32 v[10:11], s[22:23], v5, s22, v[2:3]
	global_load_dword v5, v[10:11], off nt
	s_and_b64 vcc, exec, s[0:1]
	s_waitcnt vmcnt(1)
	ds_write_b32 v0, v9 offset:10400
	s_cbranch_vccnz .LBB0_165
	global_load_dword v9, v[6:7], off offset:176 nt
	s_waitcnt vmcnt(0)
	v_mul_f32_e32 v5, v5, v9
.LBB0_165:
	v_add_u32_e32 v9, 48, v4
	s_movk_i32 s22, 0xc00
	v_mad_i64_i32 v[10:11], s[22:23], v9, s22, v[2:3]
	global_load_dword v9, v[10:11], off nt
	s_and_b64 vcc, exec, s[0:1]
	s_waitcnt vmcnt(1)
	ds_write_b32 v0, v5 offset:11440
	s_cbranch_vccnz .LBB0_167
	global_load_dword v5, v[6:7], off offset:192 nt
	s_waitcnt vmcnt(0)
	v_mul_f32_e32 v9, v9, v5
.LBB0_167:
	v_add_u32_e32 v5, 52, v4
	s_movk_i32 s22, 0xc00
	v_mad_i64_i32 v[10:11], s[22:23], v5, s22, v[2:3]
	global_load_dword v5, v[10:11], off nt
	s_and_b64 vcc, exec, s[0:1]
	s_waitcnt vmcnt(1)
	ds_write_b32 v0, v9 offset:12480
	s_cbranch_vccnz .LBB0_169
	global_load_dword v9, v[6:7], off offset:208 nt
	s_waitcnt vmcnt(0)
	v_mul_f32_e32 v5, v5, v9
.LBB0_169:
	v_add_u32_e32 v9, 56, v4
	s_movk_i32 s22, 0xc00
	v_mad_i64_i32 v[10:11], s[22:23], v9, s22, v[2:3]
	global_load_dword v9, v[10:11], off nt
	s_and_b64 vcc, exec, s[0:1]
	s_waitcnt vmcnt(1)
	ds_write_b32 v0, v5 offset:13520
	s_cbranch_vccnz .LBB0_171
	global_load_dword v5, v[6:7], off offset:224 nt
	s_waitcnt vmcnt(0)
	v_mul_f32_e32 v9, v9, v5
